# up phase: accumulators zeroed by 8 MFMAs on zero operands instead of 128 v_mov per unit
# speedup vs baseline: 1.0039x; 1.0020x over previous
.LBB0_46:
	s_mov_b32 s7, 16
	s_cmp_lt_i32 s7, 1
	s_cbranch_scc1 .LBB0_62
	s_add_i32 s33, s7, -2
	s_add_u32 s68, s8, 0x100
	s_addc_u32 s69, s9, 0
	s_add_u32 s4, s4, 0x40080
	v_mov_b32_e32 v128, 0
	v_mov_b32_e32 v129, 0
	v_mov_b32_e32 v130, 0
	v_mov_b32_e32 v131, 0
	s_mov_b64 s[84:85], s[54:55]
	s_addc_u32 s5, s5, 0
	s_mov_b32 s8, 0
	s_nop 1
	v_mfma_f32_32x32x16_bf16 v[0:15], v[128:131], v[128:131], 0
	v_mfma_f32_32x32x16_bf16 v[16:31], v[128:131], v[128:131], 0
	v_mfma_f32_32x32x16_bf16 v[32:47], v[128:131], v[128:131], 0
	v_mfma_f32_32x32x16_bf16 v[48:63], v[128:131], v[128:131], 0
	v_mfma_f32_32x32x16_bf16 v[64:79], v[128:131], v[128:131], 0
	v_mfma_f32_32x32x16_bf16 v[80:95], v[128:131], v[128:131], 0
	v_mfma_f32_32x32x16_bf16 v[96:111], v[128:131], v[128:131], 0
	v_mfma_f32_32x32x16_bf16 v[112:127], v[128:131], v[128:131], 0
